# FINAL phase row loop rewritten: gains loaded once, next row's sums and x chunks requested during the current row's arithmetic, one counted wait per row (was 5 serial waits per row); on top of peel + H
# speedup vs baseline: 1.0043x; 1.0043x over previous
; __device__ __forceinline__ float bperm(float v, int src_lane) { return __int_as_float(__builtin_amdgcn_ds_bpermute(src_lane << 2, __float_as_int(v))); }
; __global__ void __launch_bounds__(NTHR, 2) mk_fwd(MKArgs args) {
;     ...
;         for (int row = byg ? 2048 * (cid & 7) + (cid >> 3) * NWAVES + wv : cid * NWAVES + wv; row < (byg ? 2048 * (cid & 7) + 2048 : M); row += (byg ? 32 : G) * NWAVES) {
;             float s = (lane < 32) ? RSS1[(size_t)row * 32 + lane] : 0.f;
; #pragma unroll
;             for (int o = 32; o >= 1; o >>= 1) s += bperm(s, lane ^ o);
;             const float r = rsqrtf(s * (1.f / D) + EPS);
;             float* orow = args.out + (size_t)row * D; const bf16_t* xrow = X + (size_t)row * D;
; #pragma unroll
;             for (int j = 0; j < 4; ++j) { const int c = j * 512 + lane * 8; const f16x8_t hh = *(const f16x8_t*)(xrow + c); const f32x8_t ff = __builtin_convertvector(hh, f32x8_t);
;                 const f32x4 g0 = *(const f32x4*)(fin_g + c), g1 = *(const f32x4*)(fin_g + c + 4);
;                 *(f32x4*)(orow + c) = (f32x4){ff[0], ff[1], ff[2], ff[3]} * r * g0; *(f32x4*)(orow + c + 4) = (f32x4){ff[4], ff[5], ff[6], ff[7]} * r * g1; }
;         }
.Lfin_pre:
	global_load_dwordx4 v[48:51], v[0:1], off
	global_load_dwordx4 v[52:55], v[0:1], off offset:16
	global_load_dwordx4 v[56:59], v[0:1], off offset:2048
	global_load_dwordx4 v[60:63], v[0:1], off offset:2064
	global_load_dwordx4 v[64:67], v[2:3], off
	global_load_dwordx4 v[68:71], v[2:3], off offset:16
	global_load_dwordx4 v[72:75], v[4:5], off
	global_load_dwordx4 v[76:79], v[4:5], off offset:16
	v_mov_b32_e32 v19, 0
	s_and_saveexec_b64 s[0:1], vcc
	global_load_dword v19, v[6:7], off
	s_or_b64 exec, exec, s[0:1]
	global_load_dwordx4 v[80:83], v[10:11], off
	s_mov_b64 s[100:101], 0x4000
	v_lshl_add_u64 v[46:47], v[10:11], 0, s[100:101]
	global_load_dwordx4 v[84:87], v[46:47], off
	s_mov_b64 s[100:101], 0x8000
	v_lshl_add_u64 v[46:47], v[10:11], 0, s[100:101]
	global_load_dwordx4 v[88:91], v[46:47], off
	s_mov_b64 s[100:101], 0xc000
	v_lshl_add_u64 v[46:47], v[10:11], 0, s[100:101]
	global_load_dwordx4 v[92:95], v[46:47], off
	s_waitcnt vmcnt(0)
.Lfin_loop:
	ds_bpermute_b32 v32, v12, v19
	s_waitcnt lgkmcnt(0)
	v_add_f32_e32 v19, v19, v32
	ds_bpermute_b32 v32, v13, v19
	s_waitcnt lgkmcnt(0)
	v_add_f32_e32 v19, v19, v32
	ds_bpermute_b32 v32, v14, v19
	s_waitcnt lgkmcnt(0)
	v_add_f32_e32 v19, v19, v32
	ds_bpermute_b32 v32, v15, v19
	s_waitcnt lgkmcnt(0)
	v_add_f32_e32 v19, v19, v32
	ds_bpermute_b32 v32, v16, v19
	s_waitcnt lgkmcnt(0)
	v_add_f32_e32 v19, v19, v32
	ds_bpermute_b32 v32, v17, v19
	s_waitcnt lgkmcnt(0)
	v_add_f32_e32 v19, v19, v32
	v_fmamk_f32 v19, v19, 0x3a000000, v18
	v_mul_f32_e32 v32, 0x4b800000, v19
	v_cmp_gt_f32_e64 s[0:1], s3, v19
	v_cvt_f32_f16_e32 v96, v80
	v_cvt_f32_f16_sdwa v97, v80 dst_sel:DWORD dst_unused:UNUSED_PAD src0_sel:WORD_1
	v_cndmask_b32_e64 v19, v19, v32, s[0:1]
	v_rsq_f32_e32 v19, v19
	v_cvt_f32_f16_e32 v98, v81
	v_cvt_f32_f16_sdwa v99, v81 dst_sel:DWORD dst_unused:UNUSED_PAD src0_sel:WORD_1
	v_cvt_f32_f16_e32 v100, v82
	v_cvt_f32_f16_sdwa v101, v82 dst_sel:DWORD dst_unused:UNUSED_PAD src0_sel:WORD_1
	v_cvt_f32_f16_e32 v102, v83
	v_cvt_f32_f16_sdwa v103, v83 dst_sel:DWORD dst_unused:UNUSED_PAD src0_sel:WORD_1
	v_cvt_f32_f16_e32 v104, v84
	v_cvt_f32_f16_sdwa v105, v84 dst_sel:DWORD dst_unused:UNUSED_PAD src0_sel:WORD_1
	v_cvt_f32_f16_e32 v106, v85
	v_cvt_f32_f16_sdwa v107, v85 dst_sel:DWORD dst_unused:UNUSED_PAD src0_sel:WORD_1
	v_cvt_f32_f16_e32 v108, v86
	v_cvt_f32_f16_sdwa v109, v86 dst_sel:DWORD dst_unused:UNUSED_PAD src0_sel:WORD_1
	v_cvt_f32_f16_e32 v110, v87
	v_cvt_f32_f16_sdwa v111, v87 dst_sel:DWORD dst_unused:UNUSED_PAD src0_sel:WORD_1
	v_mul_f32_e32 v32, 0x45800000, v19
	v_cndmask_b32_e64 v32, v19, v32, s[0:1]
	v_cvt_f32_f16_e32 v112, v88
	v_cvt_f32_f16_sdwa v113, v88 dst_sel:DWORD dst_unused:UNUSED_PAD src0_sel:WORD_1
	v_cvt_f32_f16_e32 v114, v89
	v_cvt_f32_f16_sdwa v115, v89 dst_sel:DWORD dst_unused:UNUSED_PAD src0_sel:WORD_1
	v_cvt_f32_f16_e32 v116, v90
	v_cvt_f32_f16_sdwa v117, v90 dst_sel:DWORD dst_unused:UNUSED_PAD src0_sel:WORD_1
	v_cvt_f32_f16_e32 v118, v91
	v_cvt_f32_f16_sdwa v119, v91 dst_sel:DWORD dst_unused:UNUSED_PAD src0_sel:WORD_1
	v_cvt_f32_f16_e32 v120, v92
	v_cvt_f32_f16_sdwa v121, v92 dst_sel:DWORD dst_unused:UNUSED_PAD src0_sel:WORD_1
	v_cvt_f32_f16_e32 v122, v93
	v_cvt_f32_f16_sdwa v123, v93 dst_sel:DWORD dst_unused:UNUSED_PAD src0_sel:WORD_1
	v_cvt_f32_f16_e32 v124, v94
	v_cvt_f32_f16_sdwa v125, v94 dst_sel:DWORD dst_unused:UNUSED_PAD src0_sel:WORD_1
	v_cvt_f32_f16_e32 v126, v95
	v_cvt_f32_f16_sdwa v127, v95 dst_sel:DWORD dst_unused:UNUSED_PAD src0_sel:WORD_1
	s_add_i32 s10, s10, s2
	v_lshl_add_u64 v[6:7], v[6:7], 0, s[4:5]
	v_lshl_add_u64 v[10:11], v[10:11], 0, s[8:9]
	s_cmp_lt_i32 s10, s11
	s_cbranch_scc0 .Lfin_nopf
	v_mov_b32_e32 v19, 0
	s_and_saveexec_b64 s[0:1], vcc
	global_load_dword v19, v[6:7], off
	s_or_b64 exec, exec, s[0:1]
	global_load_dwordx4 v[80:83], v[10:11], off
	s_mov_b64 s[100:101], 0x4000
	v_lshl_add_u64 v[46:47], v[10:11], 0, s[100:101]
	global_load_dwordx4 v[84:87], v[46:47], off
	s_mov_b64 s[100:101], 0x8000
	v_lshl_add_u64 v[46:47], v[10:11], 0, s[100:101]
	global_load_dwordx4 v[88:91], v[46:47], off
	s_mov_b64 s[100:101], 0xc000
	v_lshl_add_u64 v[46:47], v[10:11], 0, s[100:101]
	global_load_dwordx4 v[92:95], v[46:47], off
.Lfin_nopf:
	v_pk_mul_f32 v[96:97], v[32:33], v[96:97] op_sel_hi:[0,1]
	v_pk_mul_f32 v[98:99], v[32:33], v[98:99] op_sel_hi:[0,1]
	v_pk_mul_f32 v[100:101], v[32:33], v[100:101] op_sel_hi:[0,1]
	v_pk_mul_f32 v[102:103], v[32:33], v[102:103] op_sel_hi:[0,1]
	v_pk_mul_f32 v[96:97], v[48:49], v[96:97]
	v_pk_mul_f32 v[98:99], v[50:51], v[98:99]
	v_pk_mul_f32 v[100:101], v[52:53], v[100:101]
	v_pk_mul_f32 v[102:103], v[54:55], v[102:103]
	global_store_dwordx4 v[8:9], v[96:99], off offset:-4096
	global_store_dwordx4 v[8:9], v[100:103], off offset:-4080
	v_pk_mul_f32 v[104:105], v[32:33], v[104:105] op_sel_hi:[0,1]
	v_pk_mul_f32 v[106:107], v[32:33], v[106:107] op_sel_hi:[0,1]
	v_pk_mul_f32 v[108:109], v[32:33], v[108:109] op_sel_hi:[0,1]
	v_pk_mul_f32 v[110:111], v[32:33], v[110:111] op_sel_hi:[0,1]
	v_pk_mul_f32 v[104:105], v[56:57], v[104:105]
	v_pk_mul_f32 v[106:107], v[58:59], v[106:107]
	v_pk_mul_f32 v[108:109], v[60:61], v[108:109]
	v_pk_mul_f32 v[110:111], v[62:63], v[110:111]
	global_store_dwordx4 v[8:9], v[104:107], off offset:-2048
	global_store_dwordx4 v[8:9], v[108:111], off offset:-2032
	v_pk_mul_f32 v[112:113], v[32:33], v[112:113] op_sel_hi:[0,1]
	v_pk_mul_f32 v[114:115], v[32:33], v[114:115] op_sel_hi:[0,1]
	v_pk_mul_f32 v[116:117], v[32:33], v[116:117] op_sel_hi:[0,1]
	v_pk_mul_f32 v[118:119], v[32:33], v[118:119] op_sel_hi:[0,1]
	v_pk_mul_f32 v[112:113], v[64:65], v[112:113]
	v_pk_mul_f32 v[114:115], v[66:67], v[114:115]
	v_pk_mul_f32 v[116:117], v[68:69], v[116:117]
	v_pk_mul_f32 v[118:119], v[70:71], v[118:119]
	global_store_dwordx4 v[8:9], v[112:115], off
	global_store_dwordx4 v[8:9], v[116:119], off offset:16
	v_pk_mul_f32 v[120:121], v[32:33], v[120:121] op_sel_hi:[0,1]
	v_pk_mul_f32 v[122:123], v[32:33], v[122:123] op_sel_hi:[0,1]
	v_pk_mul_f32 v[124:125], v[32:33], v[124:125] op_sel_hi:[0,1]
	v_pk_mul_f32 v[126:127], v[32:33], v[126:127] op_sel_hi:[0,1]
	v_pk_mul_f32 v[120:121], v[72:73], v[120:121]
	v_pk_mul_f32 v[122:123], v[74:75], v[122:123]
	v_pk_mul_f32 v[124:125], v[76:77], v[124:125]
	v_pk_mul_f32 v[126:127], v[78:79], v[126:127]
	global_store_dwordx4 v[8:9], v[120:123], off offset:2048
	global_store_dwordx4 v[8:9], v[124:127], off offset:2064
	v_lshl_add_u64 v[8:9], v[8:9], 0, s[6:7]
	s_cmp_lt_i32 s10, s11
	s_cbranch_scc0 .LBB0_1601
	s_waitcnt vmcnt(8)
	s_branch .Lfin_loop
